# v60 + attention loop trimmed: 8 LDS-DMA pieces share two SGPR base pairs (instruction offset / second offset VGPR), m0 writes hoisted so no s_nop pads, v_max canonicalisations and add-0 folded
# speedup vs baseline: 1.0009x; 1.0009x over previous
; __device__ __forceinline__ void attn_unit(const bf16* __restrict__ qkvb, int seq, int q0, int h, ldsp_t ldsb, float* wsc, const float* tab, float lam) {
;   int tid_ = threadIdx.x; asm volatile("" : "+v"(tid_));
;   const int tid = tid_, wid = __builtin_amdgcn_readfirstlane(tid >> 6), lane = tid & 63, r32 = lane & 31, hi = lane >> 5, mapw = wid >> 2, rg = wid & 3;
;   float* ws = wsc + wid * 64; float* li_l = ws; float* al_l = ws + 32;
;   float m_reg = -1e30f, l_reg = 0; bf16x8 qr[8]; f32x16 o[8];
; #pragma unroll
;   for (int d = 0; d < 8; ++d) o[d] = f32x16{};
;   const int q0w = q0 + rg * 32;
;   const bf16* Qw = qkvb + (long)(q0w + r32) * LD + h * 256 + mapw * 128 + hi * 8;
; #pragma unroll
;   for (int d0 = 0; d0 < 8; ++d0) qr[d0] = *reinterpret_cast<const bf16x8*>(Qw + d0 * 16);
;   unsigned koff0, voff0;
;   { const int row = 4 * wid + (lane >> 4), c = (lane & 15) ^ (row & 15); koff0 = (unsigned)(row * LD + 2048 + h * 256 + c * 8) * 2u; }
;   { const int subt = 2 * wid + (lane >> 5), kk = ((subt >> 3) << 3) | ((lane & 31) >> 2), key = (kk & ~0xC) | ((kk & 4) << 1) | ((kk & 8) >> 1), col = (subt & 7) * 32 + 8 * (lane & 3);
;     voff0 = (unsigned)(key * LD + 4096 + h * 256 + col) * 2u; }
;   const char* kvb = (const char*)qkvb;
;   const long tstep = 64L * LD * 2;
;     ...
;   const int NT = seq / 64;
;   const float cL = __int_as_float(__builtin_amdgcn_readfirstlane(__float_as_int(tab[0]))), cR = __int_as_float(__builtin_amdgcn_readfirstlane(__float_as_int(tab[256])));
;   ldsc_t kp[4];
; #pragma unroll
;   for (int d = 0; d < 4; ++d) kp[d] = (ldsc_t)ldsb + (mapw * 16384 + r32 * 256 + ((d * 32 + hi * 16) ^ ((r32 & 15) << 4)));
;   const int kd = (r32 & 8) ? -128 : 128;
;   const ldsc_t vp = (ldsc_t)ldsb + (V_OFF + v_rd_base(lane));
;   { _Pragma("unroll") for (int i = 0; i < 4; ++i) { DMA_K1(kvb, 0, i); DMA_V1(kvb, 0, i); } }
; __global__ void __launch_bounds__(NWAVES * 64, 2) fwd_kernel(Args args) {
;     ...
;             for (int ui = 0; ui < 4; ++ui) {
;                 const int uid = ui * F.G + F.vcu; if (uid >= Bc * 8 * nqb) break;
;                 const int bh = uid >> lgN2, qb = uid & (nqb - 1), b = bh >> 3, h = bh & 7;
;                 att3::attn_unit((const att3::bf16*)P_QKV + (size_t)b * S * QKVW, S, qb * 128, h, F.lds + RING_OFF, (float*)(lds + WSC_OFF), (const float*)(lds + TAB_OFF) + h * 260, lamfull);
.LBB0_546:
	s_mul_i32 s6, s13, s97
	s_add_i32 s6, s6, s33
	s_cmp_ge_i32 s6, s10
	s_mov_b64 s[4:5], -1
	s_cbranch_scc1 .LBB0_545
	s_ashr_i32 s5, s6, s42
	s_and_b32 s14, s6, s51
	s_mov_b32 s6, 22
	s_ashr_i32 s7, s6, 31
	s_ashr_i32 s4, s5, 3
	s_and_b32 s18, s5, 7
	s_lshl_b64 s[6:7], s[6:7], 3
	s_add_u32 s6, s0, s6
	s_addc_u32 s7, s1, s7
	s_load_dwordx2 s[8:9], s[6:7], 0x0
	s_ashr_i32 s5, s4, 31
	s_lshl_b64 s[6:7], s[4:5], s43
	s_mul_i32 s4, s7, 0x3000
	s_mul_hi_u32 s5, s6, 0x3000
	s_add_i32 s5, s5, s4
	s_mul_i32 s4, s6, 0x3000
	v_mov_b32_e32 v1, v245
	s_waitcnt lgkmcnt(0)
	s_add_u32 s8, s8, s4
	s_addc_u32 s9, s9, s5
	v_readfirstlane_b32 s16, v1
	s_mul_i32 s4, s18, 0x410
	s_ashr_i32 s24, s16, 6
	s_add_i32 s20, s4, 0
	s_lshl_b32 s4, s24, 5
	s_lshl_b32 s14, s14, 7
	s_and_b32 s17, s4, 0x60
	v_and_b32_e32 v247, 31, v1
	s_or_b32 s21, s17, s14
	v_or_b32_e32 v2, s21, v247
	v_mul_u32_u24_e32 v2, 0x1800, v2
	s_ashr_i32 s25, s16, 8
	v_lshlrev_b32_e32 v226, 1, v2
	v_lshl_add_u64 v[2:3], s[8:9], 0, v[226:227]
	s_lshl_b32 s84, s18, 9
	s_lshl_b32 s4, s25, 7
	v_lshl_add_u64 v[2:3], v[2:3], 0, s[84:85]
	s_ashr_i32 s5, s4, 31
	v_lshl_add_u64 v[2:3], s[4:5], 1, v[2:3]
	s_lshl_b32 s4, s24, 2
	v_bfe_u32 v10, v1, 4, 2
	v_bfe_u32 v248, v1, 5, 1
	v_bitop3_b32 v5, s4, v1, v10 bitop3:0x36
	v_lshlrev_b32_e32 v236, 4, v248
	v_mov_b32_e32 v237, v227
	v_or_b32_e32 v4, s4, v10
	v_lshlrev_b32_e32 v5, 3, v5
	s_lshl_b32 s4, s24, 1
	s_lshl_b32 s15, s18, 8
	v_lshl_add_u64 v[2:3], v[2:3], 0, v[236:237]
	v_mul_lo_u32 v4, v4, s67
	v_and_b32_e32 v11, 0x78, v5
	s_and_b32 s5, s4, 0x1ffff0
	v_lshrrev_b32_e32 v5, 1, v1
	v_or3_b32 v6, v4, v11, s15
	v_bfe_u32 v4, v1, 2, 2
	s_and_b32 s18, s24, 4
	global_load_dwordx4 v[162:165], v[2:3], off offset:224
	global_load_dwordx4 v[166:169], v[2:3], off offset:192
	global_load_dwordx4 v[170:173], v[2:3], off offset:160
	global_load_dwordx4 v[174:177], v[2:3], off offset:128
	global_load_dwordx4 v[178:181], v[2:3], off offset:96
	global_load_dwordx4 v[182:185], v[2:3], off offset:64
	global_load_dwordx4 v[186:189], v[2:3], off offset:32
	global_load_dwordx4 v[190:193], v[2:3], off
	v_and_or_b32 v2, v5, 8, s5
	v_or3_b32 v2, s18, v4, v2
	v_and_or_b32 v7, s4, 6, v248
	v_lshlrev_b32_e32 v8, 3, v1
	v_mul_u32_u24_e32 v2, 0x1800, v2
	s_lshl_b32 s4, s24, 10
	s_add_i32 s20, s20, 0x20a00
	v_lshlrev_b32_e32 v7, 5, v7
	v_and_b32_e32 v12, 24, v8
	v_or_b32_e32 v13, s15, v2
	v_mov_b32_e32 v15, 0x1000
	s_add_i32 s23, s4, 0
	v_or3_b32 v2, v7, v12, v13
	v_mov_b32_e32 v14, 0x2000
	v_mov_b32_e32 v3, s20
	v_lshl_add_u32 v226, v6, 1, v15
	s_mov_b32 m0, s23
	v_lshl_add_u32 v2, v2, 1, v14
	ds_read2st64_b32 v[4:5], v3 offset1:4
	v_lshl_add_u64 v[6:7], s[8:9], 0, v[226:227]
	v_mov_b32_e32 v3, v227
	global_load_lds_dwordx4 v226, s[8:9]
	s_add_i32 m0, s23, 0x8000
	v_lshl_add_u64 v[8:9], s[8:9], 0, v[2:3]
	global_load_lds_dwordx4 v2, s[8:9]
	v_lshl_add_u64 v[2:3], v[6:7], 0, s[90:91]
	s_add_i32 m0, s23, 0x2000
	s_mov_b64 s[4:5], 0x30000
	global_load_lds_dwordx4 v[2:3], off
	v_lshl_add_u64 v[2:3], v[8:9], 0, s[4:5]
	s_add_i32 m0, s23, 0xa000
	s_mov_b64 s[4:5], 0x100
	global_load_lds_dwordx4 v[2:3], off
	v_lshl_add_u64 v[2:3], v[6:7], 0, s[4:5]
	s_add_i32 m0, s23, 0x4000
	s_mov_b64 s[4:5], 0x60100
	global_load_lds_dwordx4 v[2:3], off
	v_lshl_add_u64 v[2:3], v[8:9], 0, s[90:91]
	s_add_i32 m0, s23, 0xc000
	s_waitcnt lgkmcnt(0)
	v_readfirstlane_b32 s19, v4
	global_load_lds_dwordx4 v[2:3], off
	v_lshl_add_u64 v[2:3], v[6:7], 0, s[4:5]
	s_add_i32 m0, s23, 0x6000
	s_mov_b64 s[4:5], 0x90000
	global_load_lds_dwordx4 v[2:3], off
	v_lshl_add_u64 v[2:3], v[8:9], 0, s[4:5]
	s_add_i32 m0, s23, 0xe000
	s_and_b32 s4, s16, 0x3fffffc0
	global_load_lds_dwordx4 v[2:3], off
	s_lshl_b32 s4, s4, 2
	s_add_i32 s18, s4, 0
	s_lshl_b32 s4, s25, 14
	v_lshlrev_b32_e32 v3, 4, v1
	s_add_i32 s4, s4, 0
	v_readfirstlane_b32 s22, v5
	v_and_b32_e32 v4, 0xf0, v3
	v_lshl_add_u32 v5, v247, 8, s4
	v_or_b32_e32 v6, 32, v236
	v_xad_u32 v253, v6, v4, v5
	v_or_b32_e32 v6, 64, v236
	v_and_b32_e32 v2, 63, v1
	v_xad_u32 v241, v6, v4, v5
	v_or_b32_e32 v6, 0x60, v236
	v_xad_u32 v252, v236, v4, v5
	v_xad_u32 v244, v6, v4, v5
	v_lshlrev_b32_e32 v5, 3, v2
	s_and_b32 s4, s24, 3
	v_and_b32_e32 v6, 24, v5
	v_and_b32_e32 v3, 0xc0, v3
	v_lshlrev_b32_e32 v7, 1, v1
	s_lshl_b32 s5, s4, 5
	v_and_b32_e32 v4, 8, v1
	v_and_b32_e32 v7, 32, v7
	v_and_b32_e32 v5, 0x100, v5
	v_add3_u32 v3, 0, v6, v3
	s_or_b32 s5, s5, s14
	v_add3_u32 v250, v3, v7, v5
	v_cmp_eq_u32_e32 vcc, 0, v4
	v_mov_b32_e32 v3, 0xffffff80
	v_mov_b32_e32 v4, 0x80
	s_sub_i32 s26, 0, s5
	s_mul_i32 s5, s24, 0x6000
	v_cndmask_b32_e32 v251, v3, v4, vcc
	v_cmp_gt_u32_e32 vcc, 32, v2
	v_mov_b32_e32 v2, s5
	v_mad_u32_u24 v2, v10, s67, v2
	v_or3_b32 v2, v2, s15, v11
	v_lshl_add_u32 v226, v2, 1, v15
	v_lshl_or_b32 v2, s4, 6, v13
	v_and_b32_e32 v1, 32, v1
	s_waitcnt vmcnt(0)
	s_waitcnt vmcnt(0)
; __device__ __forceinline__ void attn_unit(const bf16* __restrict__ qkvb, int seq, int q0, int h, ldsp_t ldsb, float* wsc, const float* tab, float lam) {
;     ...
;   float* ws = wsc + wid * 64; float* li_l = ws; float* al_l = ws + 32;
;   float m_reg = -1e30f, l_reg = 0; bf16x8 qr[8]; f32x16 o[8];
; #pragma unroll
;   for (int d = 0; d < 8; ++d) o[d] = f32x16{};
;   const int q0w = q0 + rg * 32;
;   const bf16* Qw = qkvb + (long)(q0w + r32) * LD + h * 256 + mapw * 128 + hi * 8;
; #pragma unroll
;   for (int d0 = 0; d0 < 8; ++d0) qr[d0] = *reinterpret_cast<const bf16x8*>(Qw + d0 * 16);
;   unsigned koff0, voff0;
;   { const int row = 4 * wid + (lane >> 4), c = (lane & 15) ^ (row & 15); koff0 = (unsigned)(row * LD + 2048 + h * 256 + c * 8) * 2u; }
;   { const int subt = 2 * wid + (lane >> 5), kk = ((subt >> 3) << 3) | ((lane & 31) >> 2), key = (kk & ~0xC) | ((kk & 4) << 1) | ((kk & 8) >> 1), col = (subt & 7) * 32 + 8 * (lane & 3);
;     voff0 = (unsigned)(key * LD + 4096 + h * 256 + col) * 2u; }
	v_lshlrev_b32_e32 v3, 2, v248
	v_or3_b32 v1, v2, v1, v12
	v_mov_b32_e32 v98, v227
	v_mov_b32_e32 v99, v227
	v_mov_b32_e32 v112, v227
	v_mov_b32_e32 v113, v227
	v_mov_b32_e32 v0, v245
	s_add_i32 s18, s18, 0x20200
	v_sub_u32_e32 v245, v3, v247
	v_lshl_add_u32 v238, v1, 1, v14
	v_mov_b32_e32 v100, v227
	v_mov_b32_e32 v101, v227
	v_mov_b32_e32 v102, v227
	v_mov_b32_e32 v103, v227
	v_mov_b32_e32 v104, v227
	v_mov_b32_e32 v105, v227
	v_mov_b32_e32 v106, v227
	v_mov_b32_e32 v107, v227
	v_mov_b32_e32 v108, v227
	v_mov_b32_e32 v109, v227
	v_mov_b32_e32 v110, v227
	v_mov_b32_e32 v111, v227
	v_mov_b64_e32 v[128:129], v[112:113]
	v_mov_b64_e32 v[66:67], v[98:99]
	v_mov_b64_e32 v[82:83], v[98:99]
	v_mov_b64_e32 v[34:35], v[98:99]
	v_mov_b64_e32 v[50:51], v[98:99]
	v_mov_b64_e32 v[18:19], v[98:99]
	v_mov_b64_e32 v[2:3], v[98:99]
	v_mov_b32_e32 v242, 0x80008000
	v_mov_b32_e32 v246, 0x260
	v_mov_b32_e32 v240, 0x3727c5ac
	s_mov_b32 s25, 0
	v_lshl_add_u32 v237, v247, 2, s18
	v_mov_b32_e32 v239, v227
	v_mov_b32_e32 v249, 0
	v_mov_b32_e32 v211, 0xf149f2ca
	s_mov_b32 s27, 0x10000
	v_mov_b64_e32 v[126:127], v[110:111]
	v_mov_b64_e32 v[124:125], v[108:109]
	v_mov_b64_e32 v[122:123], v[106:107]
	v_mov_b64_e32 v[120:121], v[104:105]
	v_mov_b64_e32 v[118:119], v[102:103]
	v_mov_b64_e32 v[116:117], v[100:101]
	v_mov_b64_e32 v[114:115], v[98:99]
	v_mov_b64_e32 v[68:69], v[100:101]
	v_mov_b64_e32 v[70:71], v[102:103]
	v_mov_b64_e32 v[72:73], v[104:105]
	v_mov_b64_e32 v[74:75], v[106:107]
	v_mov_b64_e32 v[76:77], v[108:109]
	v_mov_b64_e32 v[78:79], v[110:111]
	v_mov_b64_e32 v[80:81], v[112:113]
	v_mov_b64_e32 v[84:85], v[100:101]
	v_mov_b64_e32 v[86:87], v[102:103]
	v_mov_b64_e32 v[88:89], v[104:105]
	v_mov_b64_e32 v[90:91], v[106:107]
	v_mov_b64_e32 v[92:93], v[108:109]
	v_mov_b64_e32 v[94:95], v[110:111]
	v_mov_b64_e32 v[96:97], v[112:113]
	v_mov_b64_e32 v[36:37], v[100:101]
	v_mov_b64_e32 v[38:39], v[102:103]
	v_mov_b64_e32 v[40:41], v[104:105]
	v_mov_b64_e32 v[42:43], v[106:107]
	v_mov_b64_e32 v[44:45], v[108:109]
	v_mov_b64_e32 v[46:47], v[110:111]
	v_mov_b64_e32 v[48:49], v[112:113]
	v_mov_b64_e32 v[52:53], v[100:101]
	v_mov_b64_e32 v[54:55], v[102:103]
	v_mov_b64_e32 v[56:57], v[104:105]
	v_mov_b64_e32 v[58:59], v[106:107]
	v_mov_b64_e32 v[60:61], v[108:109]
	v_mov_b64_e32 v[62:63], v[110:111]
	v_mov_b64_e32 v[64:65], v[112:113]
	v_mov_b64_e32 v[20:21], v[100:101]
	v_mov_b64_e32 v[22:23], v[102:103]
	v_mov_b64_e32 v[24:25], v[104:105]
	v_mov_b64_e32 v[26:27], v[106:107]
	v_mov_b64_e32 v[28:29], v[108:109]
	v_mov_b64_e32 v[30:31], v[110:111]
	v_mov_b64_e32 v[32:33], v[112:113]
	v_mov_b64_e32 v[4:5], v[100:101]
	v_mov_b64_e32 v[6:7], v[102:103]
	v_mov_b64_e32 v[8:9], v[104:105]
	v_mov_b64_e32 v[10:11], v[106:107]
	v_mov_b64_e32 v[12:13], v[108:109]
	v_mov_b64_e32 v[14:15], v[110:111]
	v_mov_b64_e32 v[16:17], v[112:113]
	v_add_u32_e32 v239, 0x30000, v238
; #define SBAR() __builtin_amdgcn_sched_barrier(0)
; #define KF(a, o) (*(const __attribute__((address_space(3))) bf16x8*)((a) + (o)))
; template <class Hook> __device__ __forceinline__ void qk_sub(f32x16& p, ldsc_t k0, ldsc_t k1, ldsc_t k2, ldsc_t k3, int kd, const bf16x8* qr, const Hook& hook) {
;     ...
;   SBAR();
;   bf16x8 f0 = KF(k0, 0), f1 = KF(k1, 0), f2 = KF(k2, 0), f3 = KF(k3, 0); SBAR(); __builtin_amdgcn_s_setprio(1);
;   p = __builtin_amdgcn_mfma_f32_32x32x16_bf16(f0, qr[0], f32x16{}, 0, 0, 0); f0 = KF(k0 + kd, 0); SBAR();
;   p = __builtin_amdgcn_mfma_f32_32x32x16_bf16(f1, qr[1], p, 0, 0, 0); f1 = KF(k1 + kd, 0); hook(0); SBAR();
;   p = __builtin_amdgcn_mfma_f32_32x32x16_bf16(f2, qr[2], p, 0, 0, 0); f2 = KF(k2 + kd, 0); SBAR();
;   p = __builtin_amdgcn_mfma_f32_32x32x16_bf16(f3, qr[3], p, 0, 0, 0); f3 = KF(k3 + kd, 0); hook(1); SBAR();
;   p = __builtin_amdgcn_mfma_f32_32x32x16_bf16(f0, qr[4], p, 0, 0, 0); SBAR();
;   p = __builtin_amdgcn_mfma_f32_32x32x16_bf16(f1, qr[5], p, 0, 0, 0); hook(2); SBAR();
;   p = __builtin_amdgcn_mfma_f32_32x32x16_bf16(f2, qr[6], p, 0, 0, 0); SBAR();
;   p = __builtin_amdgcn_mfma_f32_32x32x16_bf16(f3, qr[7], p, 0, 0, 0); hook(3); __builtin_amdgcn_s_setprio(0); SBAR();
; __device__ __forceinline__ void softmax_sub(f32x16& p, float& m_reg, float& l_reg, bf16x8& pa0, bf16x8& pa1, f32x16 (&o)[8], float* al_l, int r32, int hi, int dj, const float* tab, float cL, float cR) {
;     ...
;   if (dj <= -159) cb = cL;
;   else if (dj >= 159) cb = cR;
;   else { cb = 0.f; const int ib = dj - r32 + 4 * hi + 128;
; #pragma unroll
;     for (int r = 0; r < 16; ++r) { const int i0 = ib + (r & 3) + 8 * (r >> 2); p[r] += tab[min(max(i0, 0), 256)]; } }
.LBB0_548:
	s_waitcnt vmcnt(0)
	s_add_i32 s4, s27, 0xffff0000
	s_barrier
	s_and_b32 s29, s4, 0x10000
	v_add_u32_e32 v1, s29, v252
	v_add_u32_e32 v198, s29, v253
	v_add_u32_e32 v199, s29, v241
	v_add_u32_e32 v202, s29, v244
	ds_read_b128 v[130:133], v1
	ds_read_b128 v[134:137], v198
	ds_read_b128 v[138:141], v199
	ds_read_b128 v[142:145], v202
	s_setprio 1
	s_waitcnt lgkmcnt(0)
	v_mfma_f32_32x32x16_bf16 v[146:161], v[130:133], v[190:193], 0
	v_add_u32_e32 v206, v1, v251
	ds_read_b128 v[130:133], v206
	s_and_b32 s24, s27, 0x10000
	s_add_i32 s28, s23, s24
	v_add_u32_e32 v210, v198, v251
	v_mfma_f32_32x32x16_bf16 v[146:161], v[134:137], v[186:189], v[146:161]
	ds_read_b128 v[134:137], v210
	s_mov_b32 m0, s28
	s_add_u32 s4, s8, 0xc0000
	s_addc_u32 s5, s9, 0
	s_add_u32 s100, s8, 0x120000
	s_addc_u32 s101, s9, 0
	global_load_lds_dwordx4 v226, s[4:5]
	v_mfma_f32_32x32x16_bf16 v[146:161], v[138:141], v[182:185], v[146:161]
	v_add_u32_e32 v212, v199, v251
	ds_read_b128 v[138:141], v212
	v_add_u32_e32 v213, v202, v251
	v_mfma_f32_32x32x16_bf16 v[146:161], v[142:145], v[178:181], v[146:161]
	s_add_i32 m0, s28, 0x2000
	ds_read_b128 v[142:145], v213
	global_load_lds_dwordx4 v226, s[100:101]
	s_waitcnt lgkmcnt(0)
	s_add_i32 m0, s28, 0x3f00
	v_mfma_f32_32x32x16_bf16 v[146:161], v[130:133], v[174:177], v[146:161]
	global_load_lds_dwordx4 v226, s[4:5] offset:256
	v_mfma_f32_32x32x16_bf16 v[146:161], v[134:137], v[170:173], v[146:161]
	s_add_i32 m0, s28, 0x5f00
	v_mfma_f32_32x32x16_bf16 v[146:161], v[138:141], v[166:169], v[146:161]
	global_load_lds_dwordx4 v226, s[100:101] offset:256
	v_mfma_f32_32x32x16_bf16 v[146:161], v[142:145], v[162:165], v[146:161]
	s_setprio 0
	ds_read_b128 v[130:133], v1 offset:8192
	ds_read_b128 v[194:197], v198 offset:8192
	ds_read_b128 v[198:201], v199 offset:8192
	ds_read_b128 v[202:205], v202 offset:8192
	s_setprio 1
	s_waitcnt lgkmcnt(0)
	v_mfma_f32_32x32x16_bf16 v[130:145], v[130:133], v[190:193], 0
	ds_read_b128 v[206:209], v206 offset:8192
	v_mfma_f32_32x32x16_bf16 v[130:145], v[194:197], v[186:189], v[130:145]
	ds_read_b128 v[194:197], v210 offset:8192
	v_mfma_f32_32x32x16_bf16 v[130:145], v[198:201], v[182:185], v[130:145]
	ds_read_b128 v[198:201], v212 offset:8192
	v_mfma_f32_32x32x16_bf16 v[130:145], v[202:205], v[178:181], v[130:145]
	ds_read_b128 v[202:205], v213 offset:8192
	s_waitcnt lgkmcnt(0)
	v_mfma_f32_32x32x16_bf16 v[130:145], v[206:209], v[174:177], v[130:145]
	v_mfma_f32_32x32x16_bf16 v[130:145], v[194:197], v[170:173], v[130:145]
	v_mfma_f32_32x32x16_bf16 v[130:145], v[198:201], v[166:169], v[130:145]
	v_mfma_f32_32x32x16_bf16 v[130:145], v[202:205], v[162:165], v[130:145]
	s_setprio 0
	v_add_u32_e32 v1, s29, v250
	ds_read_b64_tr_b16 v[206:207], v1 offset:32768
	ds_read_b64_tr_b16 v[208:209], v1 offset:36864
	ds_read_b64_tr_b16 v[200:201], v1 offset:37376
	ds_read_b64_tr_b16 v[198:199], v1 offset:33280
	ds_read_b64_tr_b16 v[202:203], v1 offset:40960
	ds_read_b64_tr_b16 v[204:205], v1 offset:45056
	ds_read_b64_tr_b16 v[196:197], v1 offset:45568
	ds_read_b64_tr_b16 v[194:195], v1 offset:41472
	s_cmpk_lt_i32 s26, 0xff62
	s_cbranch_scc1 .LBB0_551
	s_cmpk_gt_i32 s26, 0x9e
	s_cbranch_scc1 .LBB0_552
	v_add_u32_e32 v210, s26, v245
	v_add_u32_e32 v210, 0x80, v210
	v_mov_b32_e32 v212, 0x100
	v_med3_i32 v212, v210, 0, v212
	v_lshl_add_u32 v220, v212, 2, s20
	v_max_i32_e32 v212, -1, v210
	v_add_u32_e32 v212, 1, v212
	v_min_u32_e32 v212, 0x100, v212
	v_lshl_add_u32 v221, v212, 2, s20
	v_max_i32_e32 v212, -2, v210
	v_add_u32_e32 v212, 2, v212
	v_min_u32_e32 v212, 0x100, v212
	v_lshl_add_u32 v222, v212, 2, s20
	v_max_i32_e32 v212, -3, v210
	v_add_u32_e32 v212, 3, v212
	v_min_u32_e32 v212, 0x100, v212
	v_lshl_add_u32 v223, v212, 2, s20
	v_max_i32_e32 v212, -8, v210
	v_add_u32_e32 v212, 8, v212
	v_min_u32_e32 v212, 0x100, v212
	v_lshl_add_u32 v224, v212, 2, s20
	v_max_i32_e32 v212, -9, v210
	v_add_u32_e32 v212, 9, v212
	v_min_u32_e32 v212, 0x100, v212
	v_lshl_add_u32 v225, v212, 2, s20
	v_max_i32_e32 v212, -10, v210
	v_add_u32_e32 v212, 10, v212
	v_min_u32_e32 v212, 0x100, v212
	v_lshl_add_u32 v232, v212, 2, s20
	v_max_i32_e32 v212, -11, v210
	v_add_u32_e32 v212, 11, v212
	v_min_u32_e32 v212, 0x100, v212
	v_lshl_add_u32 v233, v212, 2, s20
	v_max_i32_e32 v212, -16, v210
	v_max_i32_e32 v213, 0xffffffef, v210
	v_max_i32_e32 v214, 0xffffffee, v210
	v_max_i32_e32 v215, 0xffffffed, v210
	v_max_i32_e32 v216, 0xffffffe8, v210
	v_max_i32_e32 v217, 0xffffffe7, v210
	v_max_i32_e32 v218, 0xffffffe6, v210
	v_add_u32_e32 v212, 16, v212
	v_add_u32_e32 v213, 17, v213
	v_add_u32_e32 v214, 18, v214
	v_add_u32_e32 v215, 19, v215
	v_add_u32_e32 v216, 24, v216
	v_add_u32_e32 v217, 25, v217
	v_add_u32_e32 v218, 26, v218
	v_max_i32_e32 v210, 0xffffffe5, v210
	v_min_u32_e32 v212, 0x100, v212
	v_min_u32_e32 v213, 0x100, v213
	v_min_u32_e32 v214, 0x100, v214
	v_min_u32_e32 v215, 0x100, v215
	v_min_u32_e32 v216, 0x100, v216
	v_min_u32_e32 v217, 0x100, v217
	v_min_u32_e32 v218, 0x100, v218
	v_add_u32_e32 v210, 27, v210
	v_lshl_add_u32 v212, v212, 2, s20
	v_lshl_add_u32 v213, v213, 2, s20
	v_lshl_add_u32 v214, v214, 2, s20
	v_lshl_add_u32 v215, v215, 2, s20
	v_lshl_add_u32 v216, v216, 2, s20
	v_lshl_add_u32 v217, v217, 2, s20
	v_lshl_add_u32 v218, v218, 2, s20
	v_min_u32_e32 v210, 0x100, v210
	v_lshl_add_u32 v210, v210, 2, s20
	ds_read_b32 v212, v212
	ds_read_b32 v213, v213
	ds_read_b32 v214, v214
	ds_read_b32 v215, v215
	ds_read_b32 v216, v216
	ds_read_b32 v217, v217
	ds_read_b32 v218, v218
	ds_read_b32 v219, v210
	ds_read_b32 v220, v220
	ds_read_b32 v221, v221
	ds_read_b32 v222, v222
	ds_read_b32 v223, v223
	ds_read_b32 v224, v224
	ds_read_b32 v225, v225
	ds_read_b32 v232, v232
	ds_read_b32 v233, v233
	s_waitcnt lgkmcnt(0)
	v_pk_add_f32 v[160:161], v[160:161], v[218:219]
	v_pk_add_f32 v[158:159], v[158:159], v[216:217]
	v_pk_add_f32 v[156:157], v[156:157], v[214:215]
	v_pk_add_f32 v[154:155], v[154:155], v[212:213]
	v_pk_add_f32 v[152:153], v[152:153], v[232:233]
	v_pk_add_f32 v[150:151], v[150:151], v[224:225]
	v_pk_add_f32 v[148:149], v[148:149], v[222:223]
	v_pk_add_f32 v[146:147], v[146:147], v[220:221]
	s_mov_b32 s29, 0
	s_branch .LBB0_553

; #define SBAR() __builtin_amdgcn_sched_barrier(0)
; __device__ __forceinline__ int crow(int r, int hi) { return (r & 3) + 8 * (r >> 2) + 4 * hi; }
; __device__ __forceinline__ void softmax_sub(f32x16& p, float& m_reg, float& l_reg, bf16x8& pa0, bf16x8& pa1, f32x16 (&o)[8], float* al_l, int r32, int hi, int dj, const float* tab, float cL, float cR) {
;     ...
;   float pmax = p[0];
; #pragma unroll
;   for (int r = 1; r < 16; ++r) pmax = fmaxf(pmax, p[r]);
;   { auto rr = __builtin_amdgcn_permlane32_swap(__float_as_uint(pmax), __float_as_uint(pmax), false, false);
;     pmax = fmaxf(__uint_as_float(rr[0]), __uint_as_float(rr[1])) + cb; }
;   float mn, alpha;
;   if (__builtin_expect(__all(pmax - m_reg <= THR / SCALE), 1)) { mn = m_reg; alpha = 1.f; }
;   else { mn = fmaxf(m_reg, pmax); alpha = __builtin_amdgcn_exp2f((m_reg - mn) * C); m_reg = mn;
;     if (hi == 0) al_l[r32] = alpha; asm volatile("s_waitcnt lgkmcnt(0)" ::: "memory");
; #pragma unroll
;     for (int d = 0; d < 8; ++d)
; #pragma unroll
;       for (int r = 0; r < 16; ++r) o[d][r] *= al_l[crow(r, hi)]; }
;   const float mnC = (cb - mn) * C;
;   float ps = 0;
; #pragma unroll
;   for (int r = 0; r < 16; ++r) { p[r] = __builtin_amdgcn_exp2f(fmaf(p[r], C, mnC)); ps += p[r]; }
;   { auto rr = __builtin_amdgcn_permlane32_swap(__float_as_uint(ps), __float_as_uint(ps), false, false);
;     ps = __uint_as_float(rr[0]) + __uint_as_float(rr[1]); }
;   l_reg = l_reg * alpha + ps;
;     ...
;   PK4(p, 0, pa0); PK4(p, 8, pa1);
; template <int S, class Dma> __device__ __forceinline__ void pv_run(f32x16 (&o)[8], ldsc_t vb, VG g0, VG g1, bf16x8 pa0, bf16x8 pa1, const Dma& dma) {
;   SBAR(); __builtin_amdgcn_s_setprio(1);
;   vmma(o[0], g0, pa0, pa1); dma(0); SBAR(); g0 = vload<2, S>(vb); SBAR();
;   vmma(o[1], g1, pa0, pa1); dma(1); SBAR(); g1 = vload<3, S>(vb); SBAR();
;   vmma(o[2], g0, pa0, pa1); dma(2); SBAR(); g0 = vload<4, S>(vb); SBAR();
;   vmma(o[3], g1, pa0, pa1); dma(3); SBAR(); g1 = vload<5, S>(vb); SBAR();
;   vmma(o[4], g0, pa0, pa1); dma(4); SBAR(); g0 = vload<6, S>(vb); SBAR();
;   vmma(o[5], g1, pa0, pa1); dma(5); SBAR(); g1 = vload<7, S>(vb); SBAR();
;   vmma(o[6], g0, pa0, pa1); dma(6); SBAR(); vmma(o[7], g1, pa0, pa1); dma(7); __builtin_amdgcn_s_setprio(0); SBAR();
.LBB0_553:
	v_max_f32_e32 v210, v146, v147
	v_max3_f32 v210, v210, v148, v149
	v_max3_f32 v210, v210, v150, v151
	v_max3_f32 v210, v210, v152, v153
	v_max3_f32 v210, v210, v154, v155
	v_max3_f32 v210, v210, v156, v157
	v_max3_f32 v210, v210, v158, v159
	v_max3_f32 v210, v210, v160, v161
	v_mov_b32_e32 v212, v210
	s_nop 1
	v_permlane32_swap_b32_e32 v210, v212
	v_max_f32_e32 v210, v210, v212
	v_add_f32_e32 v210, s29, v210
	v_sub_f32_e32 v212, v210, v211
	v_cmp_ge_f32_e64 s[4:5], s60, v212
	s_cmp_eq_u64 s[4:5], exec
	v_mov_b32_e32 v243, 1.0
	s_cbranch_scc0 .LBB0_563
	v_mov_b32_e32 v210, v211
.LBB0_555:
	v_sub_f32_e32 v211, s29, v210
	v_mul_f32_e32 v211, 0x3e0293ee, v211
	v_fmamk_f32 v146, v146, 0x3e0293ee, v211
	v_exp_f32_e32 v146, v146
	v_fmamk_f32 v147, v147, 0x3e0293ee, v211
	v_exp_f32_e32 v147, v147
	v_fmamk_f32 v148, v148, 0x3e0293ee, v211
	v_exp_f32_e32 v148, v148
	v_fmamk_f32 v149, v149, 0x3e0293ee, v211
	v_exp_f32_e32 v149, v149
	v_fmamk_f32 v150, v150, 0x3e0293ee, v211
	v_exp_f32_e32 v150, v150
	v_fmamk_f32 v151, v151, 0x3e0293ee, v211
	v_add_f32_e32 v212, v147, v146
	v_exp_f32_e32 v151, v151
	v_fmamk_f32 v152, v152, 0x3e0293ee, v211
	v_add_f32_e32 v212, v148, v212
	v_exp_f32_e32 v152, v152
	v_fmamk_f32 v153, v153, 0x3e0293ee, v211
	v_add_f32_e32 v212, v149, v212
	v_exp_f32_e32 v153, v153
	v_fmamk_f32 v154, v154, 0x3e0293ee, v211
	v_add_f32_e32 v212, v150, v212
	v_exp_f32_e32 v154, v154
	v_fmamk_f32 v155, v155, 0x3e0293ee, v211
	v_add_f32_e32 v212, v151, v212
	v_exp_f32_e32 v155, v155
	v_fmamk_f32 v156, v156, 0x3e0293ee, v211
	v_add_f32_e32 v212, v152, v212
	v_exp_f32_e32 v156, v156
	v_fmamk_f32 v157, v157, 0x3e0293ee, v211
	v_add_f32_e32 v212, v153, v212
	v_exp_f32_e32 v157, v157
	v_fmamk_f32 v158, v158, 0x3e0293ee, v211
	v_add_f32_e32 v212, v154, v212
	v_exp_f32_e32 v158, v158
	v_fmamk_f32 v159, v159, 0x3e0293ee, v211
	v_add_f32_e32 v212, v155, v212
	v_exp_f32_e32 v159, v159
	v_fmamk_f32 v160, v160, 0x3e0293ee, v211
	v_add_f32_e32 v212, v156, v212
	v_exp_f32_e32 v160, v160
	v_fmac_f32_e32 v211, 0x3e0293ee, v161
	v_add_f32_e32 v212, v157, v212
	v_exp_f32_e32 v161, v211
	v_add_f32_e32 v211, v158, v212
	v_add_f32_e32 v211, v159, v211
	v_add_f32_e32 v211, v160, v211
	v_add_f32_e32 v212, v161, v211
	v_mov_b32_e32 v213, v212
	v_cvt_pk_bf16_f32 v146, v146, v147
	v_cvt_pk_bf16_f32 v147, v148, v149
	v_cvt_pk_bf16_f32 v148, v150, v151
	v_cvt_pk_bf16_f32 v149, v152, v153
	v_cvt_pk_bf16_f32 v150, v154, v155
	v_cvt_pk_bf16_f32 v151, v156, v157
	v_cvt_pk_bf16_f32 v152, v158, v159
	v_cvt_pk_bf16_f32 v153, v160, v161
	s_nop 1
	v_permlane32_swap_b32_e32 v212, v213
	v_permlane32_swap_b32_e32 v146, v148
	v_permlane32_swap_b32_e32 v147, v149
	v_permlane32_swap_b32_e32 v150, v152
	v_permlane32_swap_b32_e32 v151, v153
	s_setprio 1
	s_waitcnt lgkmcnt(0)
	v_mfma_f32_32x32x16_bf16 v[98:113], v[146:149], v[206:209], v[98:113]
	s_add_i32 m0, s28, 0x8000
	s_add_u32 s4, s8, 0xc0000
	s_addc_u32 s5, s9, 0
	global_load_lds_dwordx4 v238, s[4:5]
	v_mfma_f32_32x32x16_bf16 v[98:113], v[150:153], v[202:205], v[98:113]
	ds_read_b64_tr_b16 v[154:155], v1 offset:33792
	ds_read_b64_tr_b16 v[156:157], v1 offset:37888
	ds_read_b64_tr_b16 v[158:159], v1 offset:41984
	ds_read_b64_tr_b16 v[160:161], v1 offset:46080
	s_add_i32 m0, s28, 0xa000
	v_mfma_f32_32x32x16_bf16 v[114:129], v[146:149], v[198:201], v[114:129]
	global_load_lds_dwordx4 v239, s[4:5]
	v_mfma_f32_32x32x16_bf16 v[114:129], v[150:153], v[194:197], v[114:129]
	ds_read_b64_tr_b16 v[194:195], v1 offset:34304
	ds_read_b64_tr_b16 v[196:197], v1 offset:38400
	ds_read_b64_tr_b16 v[198:199], v1 offset:42496
	ds_read_b64_tr_b16 v[200:201], v1 offset:46592
	s_waitcnt lgkmcnt(0)
	s_add_i32 m0, s28, 0xc000
	v_mfma_f32_32x32x16_bf16 v[66:81], v[146:149], v[154:157], v[66:81]
	global_load_lds_dwordx4 v238, s[100:101]
	v_mfma_f32_32x32x16_bf16 v[66:81], v[150:153], v[158:161], v[66:81]
	ds_read_b64_tr_b16 v[154:155], v1 offset:34816
	ds_read_b64_tr_b16 v[156:157], v1 offset:38912
	ds_read_b64_tr_b16 v[158:159], v1 offset:43008
	ds_read_b64_tr_b16 v[160:161], v1 offset:47104
	s_add_i32 m0, s28, 0xe000
	v_mfma_f32_32x32x16_bf16 v[82:97], v[146:149], v[194:197], v[82:97]
	global_load_lds_dwordx4 v239, s[100:101]
	v_mfma_f32_32x32x16_bf16 v[82:97], v[150:153], v[198:201], v[82:97]
	ds_read_b64_tr_b16 v[194:195], v1 offset:35328
	ds_read_b64_tr_b16 v[196:197], v1 offset:39424
	ds_read_b64_tr_b16 v[198:199], v1 offset:43520
	ds_read_b64_tr_b16 v[200:201], v1 offset:47616
	s_waitcnt lgkmcnt(0)
	v_mfma_f32_32x32x16_bf16 v[34:49], v[146:149], v[154:157], v[34:49]
	v_mfma_f32_32x32x16_bf16 v[34:49], v[150:153], v[158:161], v[34:49]
	ds_read_b64_tr_b16 v[154:155], v1 offset:35840
	ds_read_b64_tr_b16 v[156:157], v1 offset:39936
	ds_read_b64_tr_b16 v[158:159], v1 offset:44032
	ds_read_b64_tr_b16 v[160:161], v1 offset:48128
	v_mfma_f32_32x32x16_bf16 v[50:65], v[146:149], v[194:197], v[50:65]
	v_mfma_f32_32x32x16_bf16 v[50:65], v[150:153], v[198:201], v[50:65]
	ds_read_b64_tr_b16 v[194:195], v1 offset:36352
	ds_read_b64_tr_b16 v[196:197], v1 offset:40448
	ds_read_b64_tr_b16 v[198:199], v1 offset:44544
	ds_read_b64_tr_b16 v[200:201], v1 offset:48640
	s_waitcnt lgkmcnt(0)
	v_mfma_f32_32x32x16_bf16 v[18:33], v[146:149], v[154:157], v[18:33]
	v_mfma_f32_32x32x16_bf16 v[18:33], v[150:153], v[158:161], v[18:33]
	v_mfma_f32_32x32x16_bf16 v[2:17], v[146:149], v[194:197], v[2:17]
	v_mfma_f32_32x32x16_bf16 v[2:17], v[150:153], v[198:201], v[2:17]
	s_setprio 0
	ds_read_b64_tr_b16 v[154:155], v1 offset:49152
	ds_read_b64_tr_b16 v[156:157], v1 offset:53248
	ds_read_b64_tr_b16 v[152:153], v1 offset:53760
	ds_read_b64_tr_b16 v[150:151], v1 offset:49664
	ds_read_b64_tr_b16 v[158:159], v1 offset:57344
	ds_read_b64_tr_b16 v[160:161], v1 offset:61440
	ds_read_b64_tr_b16 v[148:149], v1 offset:61952
	ds_read_b64_tr_b16 v[146:147], v1 offset:57856
	s_add_i32 s4, s26, 32
	s_cmpk_lt_i32 s4, 0xff62
	s_cbranch_scc1 .LBB0_558
; __device__ __forceinline__ void softmax_sub(f32x16& p, float& m_reg, float& l_reg, bf16x8& pa0, bf16x8& pa1, f32x16 (&o)[8], float* al_l, int r32, int hi, int dj, const float* tab, float cL, float cR) {
;     ...
;   if (dj <= -159) cb = cL;
;   else if (dj >= 159) cb = cR;
;   else { cb = 0.f; const int ib = dj - r32 + 4 * hi + 128;
; #pragma unroll
;     for (int r = 0; r < 16; ++r) { const int i0 = ib + (r & 3) + 8 * (r >> 2); p[r] += tab[min(max(i0, 0), 256)]; } }
	s_cmpk_gt_i32 s4, 0x9e
	s_cbranch_scc1 .LBB0_559
	v_add_u32_e32 v194, s26, v245
	v_add_u32_e32 v194, 0xa0, v194
	v_mov_b32_e32 v195, 0x100
	v_med3_i32 v195, v194, 0, v195
	v_lshl_add_u32 v202, v195, 2, s20
	v_max_i32_e32 v195, -1, v194
	v_add_u32_e32 v195, 1, v195
	v_min_u32_e32 v195, 0x100, v195
	v_lshl_add_u32 v203, v195, 2, s20
	v_max_i32_e32 v195, -2, v194
	v_add_u32_e32 v195, 2, v195
	v_min_u32_e32 v195, 0x100, v195
	v_lshl_add_u32 v204, v195, 2, s20
	v_max_i32_e32 v195, -3, v194
	v_add_u32_e32 v195, 3, v195
	v_min_u32_e32 v195, 0x100, v195
	v_lshl_add_u32 v205, v195, 2, s20
	v_max_i32_e32 v195, -8, v194
	v_add_u32_e32 v195, 8, v195
	v_min_u32_e32 v195, 0x100, v195
	v_lshl_add_u32 v206, v195, 2, s20
	v_max_i32_e32 v195, -9, v194
	v_add_u32_e32 v195, 9, v195
	v_min_u32_e32 v195, 0x100, v195
	v_lshl_add_u32 v207, v195, 2, s20
	v_max_i32_e32 v195, -10, v194
	v_add_u32_e32 v195, 10, v195
	v_min_u32_e32 v195, 0x100, v195
	v_lshl_add_u32 v208, v195, 2, s20
	v_max_i32_e32 v195, -11, v194
	v_add_u32_e32 v195, 11, v195
	v_min_u32_e32 v195, 0x100, v195
	v_lshl_add_u32 v209, v195, 2, s20
	v_max_i32_e32 v195, -16, v194
	v_max_i32_e32 v196, 0xffffffef, v194
	v_max_i32_e32 v197, 0xffffffee, v194
	v_max_i32_e32 v198, 0xffffffed, v194
	v_max_i32_e32 v199, 0xffffffe8, v194
	v_max_i32_e32 v200, 0xffffffe7, v194
	v_max_i32_e32 v201, 0xffffffe6, v194
	v_add_u32_e32 v195, 16, v195
	v_add_u32_e32 v196, 17, v196
	v_add_u32_e32 v197, 18, v197
	v_add_u32_e32 v198, 19, v198
	v_add_u32_e32 v199, 24, v199
	v_add_u32_e32 v200, 25, v200
	v_add_u32_e32 v201, 26, v201
	v_max_i32_e32 v194, 0xffffffe5, v194
	v_min_u32_e32 v195, 0x100, v195
	v_min_u32_e32 v196, 0x100, v196
	v_min_u32_e32 v197, 0x100, v197
	v_min_u32_e32 v198, 0x100, v198
	v_min_u32_e32 v199, 0x100, v199
	v_min_u32_e32 v200, 0x100, v200
	v_min_u32_e32 v201, 0x100, v201
	v_add_u32_e32 v194, 27, v194
	v_lshl_add_u32 v195, v195, 2, s20
	v_lshl_add_u32 v196, v196, 2, s20
	v_lshl_add_u32 v197, v197, 2, s20
	v_lshl_add_u32 v198, v198, 2, s20
	v_lshl_add_u32 v199, v199, 2, s20
	v_lshl_add_u32 v200, v200, 2, s20
	v_lshl_add_u32 v201, v201, 2, s20
	v_min_u32_e32 v194, 0x100, v194
	v_lshl_add_u32 v211, v194, 2, s20
	ds_read_b32 v194, v195
	ds_read_b32 v195, v196
	ds_read_b32 v196, v197
	ds_read_b32 v197, v198
	ds_read_b32 v198, v199
	ds_read_b32 v199, v200
	ds_read_b32 v200, v201
	ds_read_b32 v201, v211
	ds_read_b32 v202, v202
	ds_read_b32 v203, v203
	ds_read_b32 v204, v204
	ds_read_b32 v205, v205
	ds_read_b32 v206, v206
	ds_read_b32 v207, v207
	ds_read_b32 v208, v208
	ds_read_b32 v209, v209
	s_waitcnt lgkmcnt(0)
	v_pk_add_f32 v[144:145], v[144:145], v[200:201]
	v_pk_add_f32 v[142:143], v[142:143], v[198:199]
	v_pk_add_f32 v[140:141], v[140:141], v[196:197]
	v_pk_add_f32 v[138:139], v[138:139], v[194:195]
	v_pk_add_f32 v[136:137], v[136:137], v[208:209]
	v_pk_add_f32 v[134:135], v[134:135], v[206:207]
	v_pk_add_f32 v[132:133], v[132:133], v[204:205]
	v_pk_add_f32 v[130:131], v[130:131], v[202:203]
	s_mov_b32 s28, 0
	s_branch .LBB0_560

; #define SBAR() __builtin_amdgcn_sched_barrier(0)
; __device__ __forceinline__ int crow(int r, int hi) { return (r & 3) + 8 * (r >> 2) + 4 * hi; }
; __device__ __forceinline__ void softmax_sub(f32x16& p, float& m_reg, float& l_reg, bf16x8& pa0, bf16x8& pa1, f32x16 (&o)[8], float* al_l, int r32, int hi, int dj, const float* tab, float cL, float cR) {
;     ...
;   float pmax = p[0];
; #pragma unroll
;   for (int r = 1; r < 16; ++r) pmax = fmaxf(pmax, p[r]);
;   { auto rr = __builtin_amdgcn_permlane32_swap(__float_as_uint(pmax), __float_as_uint(pmax), false, false);
;     pmax = fmaxf(__uint_as_float(rr[0]), __uint_as_float(rr[1])) + cb; }
;   float mn, alpha;
;   if (__builtin_expect(__all(pmax - m_reg <= THR / SCALE), 1)) { mn = m_reg; alpha = 1.f; }
;   else { mn = fmaxf(m_reg, pmax); alpha = __builtin_amdgcn_exp2f((m_reg - mn) * C); m_reg = mn;
;     if (hi == 0) al_l[r32] = alpha; asm volatile("s_waitcnt lgkmcnt(0)" ::: "memory");
; #pragma unroll
;     for (int d = 0; d < 8; ++d)
; #pragma unroll
;       for (int r = 0; r < 16; ++r) o[d][r] *= al_l[crow(r, hi)]; }
;   const float mnC = (cb - mn) * C;
;   float ps = 0;
; #pragma unroll
;   for (int r = 0; r < 16; ++r) { p[r] = __builtin_amdgcn_exp2f(fmaf(p[r], C, mnC)); ps += p[r]; }
;   { auto rr = __builtin_amdgcn_permlane32_swap(__float_as_uint(ps), __float_as_uint(ps), false, false);
;     ps = __uint_as_float(rr[0]) + __uint_as_float(rr[1]); }
;   l_reg = l_reg * alpha + ps;
;     ...
;   PK4(p, 0, pa0); PK4(p, 8, pa1);
; template <int S, class Dma> __device__ __forceinline__ void pv_run(f32x16 (&o)[8], ldsc_t vb, VG g0, VG g1, bf16x8 pa0, bf16x8 pa1, const Dma& dma) {
;   SBAR(); __builtin_amdgcn_s_setprio(1);
;   vmma(o[0], g0, pa0, pa1); dma(0); SBAR(); g0 = vload<2, S>(vb); SBAR();
;   vmma(o[1], g1, pa0, pa1); dma(1); SBAR(); g1 = vload<3, S>(vb); SBAR();
;   vmma(o[2], g0, pa0, pa1); dma(2); SBAR(); g0 = vload<4, S>(vb); SBAR();
;   vmma(o[3], g1, pa0, pa1); dma(3); SBAR(); g1 = vload<5, S>(vb); SBAR();
;   vmma(o[4], g0, pa0, pa1); dma(4); SBAR(); g0 = vload<6, S>(vb); SBAR();
;   vmma(o[5], g1, pa0, pa1); dma(5); SBAR(); g1 = vload<7, S>(vb); SBAR();
;   vmma(o[6], g0, pa0, pa1); dma(6); SBAR(); vmma(o[7], g1, pa0, pa1); dma(7); __builtin_amdgcn_s_setprio(0); SBAR();
.LBB0_560:
	v_max_f32_e32 v194, v130, v131
	v_max3_f32 v194, v194, v132, v133
	v_max3_f32 v194, v194, v134, v135
	v_max3_f32 v194, v194, v136, v137
	v_max3_f32 v194, v194, v138, v139
	v_max3_f32 v194, v194, v140, v141
	v_max3_f32 v194, v194, v142, v143
	v_max3_f32 v194, v194, v144, v145
	v_mov_b32_e32 v195, v194
	s_nop 1
	v_permlane32_swap_b32_e32 v194, v195
	v_max_f32_e32 v194, v194, v195
	v_add_f32_e32 v194, s28, v194
	v_sub_f32_e32 v195, v194, v210
	v_cmp_ge_f32_e64 s[4:5], s60, v195
	s_cmp_eq_u64 s[4:5], exec
	v_mov_b32_e32 v214, 1.0
	s_cbranch_scc0 .LBB0_566
	v_mov_b32_e32 v211, v210
.LBB0_562:
	v_sub_f32_e32 v195, s28, v211
	v_mul_f32_e32 v195, 0x3e0293ee, v195
	v_fmamk_f32 v130, v130, 0x3e0293ee, v195
	v_exp_f32_e32 v130, v130
	v_fmamk_f32 v131, v131, 0x3e0293ee, v195
	v_exp_f32_e32 v131, v131
	v_fmamk_f32 v132, v132, 0x3e0293ee, v195
	v_exp_f32_e32 v132, v132
	v_fmamk_f32 v133, v133, 0x3e0293ee, v195
	v_exp_f32_e32 v133, v133
	v_fmamk_f32 v134, v134, 0x3e0293ee, v195
	v_exp_f32_e32 v134, v134
	v_fmamk_f32 v135, v135, 0x3e0293ee, v195
	v_add_f32_e32 v196, v131, v130
	v_exp_f32_e32 v135, v135
	v_fmamk_f32 v136, v136, 0x3e0293ee, v195
	v_add_f32_e32 v196, v132, v196
	v_exp_f32_e32 v136, v136
	v_fmamk_f32 v137, v137, 0x3e0293ee, v195
	v_add_f32_e32 v196, v133, v196
	v_exp_f32_e32 v137, v137
	v_fmamk_f32 v138, v138, 0x3e0293ee, v195
	v_add_f32_e32 v196, v134, v196
	v_exp_f32_e32 v138, v138
	v_fmamk_f32 v139, v139, 0x3e0293ee, v195
	v_add_f32_e32 v196, v135, v196
	v_exp_f32_e32 v139, v139
	v_fmamk_f32 v140, v140, 0x3e0293ee, v195
	v_add_f32_e32 v196, v136, v196
	v_exp_f32_e32 v140, v140
	v_fmamk_f32 v141, v141, 0x3e0293ee, v195
	v_add_f32_e32 v196, v137, v196
	v_exp_f32_e32 v141, v141
	v_fmamk_f32 v142, v142, 0x3e0293ee, v195
	v_add_f32_e32 v196, v138, v196
	v_exp_f32_e32 v142, v142
	v_fmamk_f32 v143, v143, 0x3e0293ee, v195
	v_add_f32_e32 v196, v139, v196
	v_exp_f32_e32 v143, v143
	v_fmamk_f32 v144, v144, 0x3e0293ee, v195
	v_add_f32_e32 v196, v140, v196
	v_exp_f32_e32 v144, v144
	v_fmac_f32_e32 v195, 0x3e0293ee, v145
	v_add_f32_e32 v196, v141, v196
	v_exp_f32_e32 v145, v195
	v_add_f32_e32 v195, v142, v196
	v_add_f32_e32 v195, v143, v195
	v_add_f32_e32 v195, v144, v195
	v_add_f32_e32 v195, v145, v195
	v_mov_b32_e32 v196, v195
	v_add_f32_e32 v194, v212, v213
	s_nop 0
	v_permlane32_swap_b32_e32 v195, v196
	v_fmac_f32_e32 v194, v249, v243
	v_add_f32_e32 v249, v195, v196
	s_add_i32 s25, s25, 1
	v_fmac_f32_e32 v249, v194, v214
	v_cvt_pk_bf16_f32 v130, v130, v131
	v_cvt_pk_bf16_f32 v131, v132, v133
	v_cvt_pk_bf16_f32 v132, v134, v135
	v_cvt_pk_bf16_f32 v133, v136, v137
	v_cvt_pk_bf16_f32 v134, v138, v139
	v_cvt_pk_bf16_f32 v135, v140, v141
	v_cvt_pk_bf16_f32 v136, v142, v143
	v_cvt_pk_bf16_f32 v137, v144, v145
	s_nop 0
	v_permlane32_swap_b32_e32 v130, v132
	v_permlane32_swap_b32_e32 v131, v133
	v_permlane32_swap_b32_e32 v134, v136
	v_permlane32_swap_b32_e32 v135, v137
	s_setprio 1
	s_waitcnt lgkmcnt(0)
	v_mfma_f32_32x32x16_bf16 v[98:113], v[130:133], v[154:157], v[98:113]
	v_mfma_f32_32x32x16_bf16 v[98:113], v[134:137], v[158:161], v[98:113]
	ds_read_b64_tr_b16 v[138:139], v1 offset:50176
	ds_read_b64_tr_b16 v[140:141], v1 offset:54272
	ds_read_b64_tr_b16 v[142:143], v1 offset:58368
	ds_read_b64_tr_b16 v[144:145], v1 offset:62464
	v_mfma_f32_32x32x16_bf16 v[114:129], v[130:133], v[150:153], v[114:129]
	v_mfma_f32_32x32x16_bf16 v[114:129], v[134:137], v[146:149], v[114:129]
	ds_read_b64_tr_b16 v[146:147], v1 offset:50688
	ds_read_b64_tr_b16 v[148:149], v1 offset:54784
	ds_read_b64_tr_b16 v[150:151], v1 offset:58880
	ds_read_b64_tr_b16 v[152:153], v1 offset:62976
	s_waitcnt lgkmcnt(0)
	v_mfma_f32_32x32x16_bf16 v[66:81], v[130:133], v[138:141], v[66:81]
	v_mfma_f32_32x32x16_bf16 v[66:81], v[134:137], v[142:145], v[66:81]
	ds_read_b64_tr_b16 v[138:139], v1 offset:51200
	ds_read_b64_tr_b16 v[140:141], v1 offset:55296
	ds_read_b64_tr_b16 v[142:143], v1 offset:59392
	ds_read_b64_tr_b16 v[144:145], v1 offset:63488
	v_mfma_f32_32x32x16_bf16 v[82:97], v[130:133], v[146:149], v[82:97]
	v_mfma_f32_32x32x16_bf16 v[82:97], v[134:137], v[150:153], v[82:97]
	ds_read_b64_tr_b16 v[146:147], v1 offset:51712
	ds_read_b64_tr_b16 v[148:149], v1 offset:55808
	ds_read_b64_tr_b16 v[150:151], v1 offset:59904
	ds_read_b64_tr_b16 v[152:153], v1 offset:64000
	s_waitcnt lgkmcnt(0)
	v_mfma_f32_32x32x16_bf16 v[34:49], v[130:133], v[138:141], v[34:49]
	v_mfma_f32_32x32x16_bf16 v[34:49], v[134:137], v[142:145], v[34:49]
	ds_read_b64_tr_b16 v[138:139], v1 offset:52224
	ds_read_b64_tr_b16 v[140:141], v1 offset:56320
	ds_read_b64_tr_b16 v[142:143], v1 offset:60416
	ds_read_b64_tr_b16 v[144:145], v1 offset:64512
	v_mfma_f32_32x32x16_bf16 v[50:65], v[130:133], v[146:149], v[50:65]
	v_mfma_f32_32x32x16_bf16 v[50:65], v[134:137], v[150:153], v[50:65]
	ds_read_b64_tr_b16 v[146:147], v1 offset:52736
	ds_read_b64_tr_b16 v[148:149], v1 offset:56832
	ds_read_b64_tr_b16 v[150:151], v1 offset:60928
	ds_read_b64_tr_b16 v[152:153], v1 offset:65024
	s_waitcnt lgkmcnt(0)
	v_mfma_f32_32x32x16_bf16 v[18:33], v[130:133], v[138:141], v[18:33]
	v_mfma_f32_32x32x16_bf16 v[18:33], v[134:137], v[142:145], v[18:33]
	v_mfma_f32_32x32x16_bf16 v[2:17], v[130:133], v[146:149], v[2:17]
	v_mfma_f32_32x32x16_bf16 v[2:17], v[134:137], v[150:153], v[2:17]
	s_setprio 0
	s_add_i32 s26, s26, 64
	s_add_i32 s27, s27, 0x10000
	s_add_u32 s8, s8, 0xc0000
	s_addc_u32 s9, s9, 0
	s_cmp_eq_u32 s11, s25
	s_cbranch_scc0 .LBB0_548
	s_branch .LBB0_569
